# GEMM main-loop heads aligned to 64 bytes (.p2align 6)
# baseline (speedup 1.0000x reference)
.LBB0_122:
	v_readfirstlane_b32 s10, v100
	v_readfirstlane_b32 s11, v101
	v_readfirstlane_b32 s12, v104
	v_readfirstlane_b32 s13, v105
	v_readfirstlane_b32 s14, v106
	v_readfirstlane_b32 s15, v107
	v_readfirstlane_b32 s16, v108
	v_readfirstlane_b32 s17, v109
	v_readfirstlane_b32 s18, v102
	v_readfirstlane_b32 s19, v103
	v_readfirstlane_b32 s20, v110
	v_readfirstlane_b32 s21, v111
	v_readfirstlane_b32 s22, v112
	v_readfirstlane_b32 s23, v113
	v_subrev_u32_e32 v140, s10, v100
	v_subrev_u32_e32 v141, s18, v102
	s_nop 4
	s_add_i32 s7, s6, 64
	s_min_u32 s8, s7, 0xae0
	s_lshl_b32 s78, s8, 1
	ds_read_b128 v[52:55], v116 offset:0
	ds_read_b128 v[48:51], v116 offset:0x800
	ds_read_b128 v[44:47], v116 offset:0x1000
	ds_read_b128 v[96:99], v114 offset:0
	ds_read_b128 v[92:95], v114 offset:0x800
	ds_read_b128 v[88:91], v114 offset:0x1000
	v_add_u32_e32 v142, s78, v140
	v_add_u32_e32 v143, s78, v141
	global_load_dwordx4 v[64:67], v142, s[10:11]
	ds_read_b128 v[56:59], v114 offset:0x1800
	global_load_dwordx4 v[60:63], v142, s[12:13]
	global_load_dwordx4 v[72:75], v142, s[14:15]
	global_load_dwordx4 v[68:71], v142, s[16:17]
	global_load_dwordx4 v[84:87], v143, s[18:19]
	s_waitcnt lgkmcnt(3)
	v_mfma_f32_32x32x16_bf16 a[48:63], v[96:99], v[52:55], 0
	ds_read_b128 v[36:39], v117 offset:0
	v_mfma_f32_32x32x16_bf16 a[64:79], v[96:99], v[48:51], 0
	global_load_dwordx4 v[76:79], v143, s[20:21]
	v_mfma_f32_32x32x16_bf16 a[80:95], v[96:99], v[44:47], 0
	ds_read_b128 v[40:43], v117 offset:0x800
	s_waitcnt lgkmcnt(4)
	v_mfma_f32_32x32x16_bf16 a[96:111], v[92:95], v[52:55], 0
	global_load_dwordx4 v[80:83], v143, s[22:23]
	v_mfma_f32_32x32x16_bf16 a[112:127], v[92:95], v[48:51], 0
	ds_read_b128 v[120:123], v117 offset:0x1000
	v_mfma_f32_32x32x16_bf16 a[128:143], v[92:95], v[44:47], 0
	ds_read_b128 v[124:127], v115 offset:0
	s_waitcnt lgkmcnt(5)
	v_mfma_f32_32x32x16_bf16 a[144:159], v[88:91], v[52:55], 0
	ds_read_b128 v[128:131], v115 offset:0x800
	s_min_u32 s6, s6, 0xa80
	s_lshl_b32 s78, s6, 1
	v_mfma_f32_32x32x16_bf16 a[160:175], v[88:91], v[48:51], 0
	ds_read_b128 v[132:135], v115 offset:0x1000
	s_add_i32 s8, s78, 0xc0
	s_mov_b32 s9, s79
	v_mfma_f32_32x32x16_bf16 a[176:191], v[88:91], v[44:47], 0
	ds_read_b128 v[136:139], v115 offset:0x1800
	s_add_i32 s5, s5, 2
	s_cmpk_lt_u32 s5, 0x56
	s_waitcnt lgkmcnt(7)
	v_mfma_f32_32x32x16_bf16 a[32:47], v[56:59], v[52:55], 0
	s_waitcnt vmcnt(13)
	ds_write_b128 v118, v[4:7] offset:0x8000
	v_mfma_f32_32x32x16_bf16 a[16:31], v[56:59], v[48:51], 0
	s_waitcnt vmcnt(12)
	ds_write_b128 v118, v[8:11] offset:0x9000
	v_mfma_f32_32x32x16_bf16 a[0:15], v[56:59], v[44:47], 0
	s_waitcnt vmcnt(11)
	ds_write_b128 v118, v[12:15] offset:0xa000
	s_waitcnt lgkmcnt(6)
	v_mfma_f32_32x32x16_bf16 a[48:63], v[124:127], v[36:39], a[48:63]
	s_waitcnt vmcnt(10)
	ds_write_b128 v118, v[16:19] offset:0xb000
	v_mfma_f32_32x32x16_bf16 a[64:79], v[124:127], v[40:43], a[64:79]
	s_waitcnt vmcnt(9)
	ds_write_b128 v118, v[20:23] offset:0xc000
	v_mfma_f32_32x32x16_bf16 a[80:95], v[124:127], v[120:123], a[80:95]
	s_waitcnt vmcnt(8)
	ds_write_b128 v118, v[24:27] offset:0xd000
	s_waitcnt lgkmcnt(8)
	v_mfma_f32_32x32x16_bf16 a[96:111], v[128:131], v[36:39], a[96:111]
	s_waitcnt vmcnt(7)
	ds_write_b128 v118, v[28:31] offset:0xe000
	v_mfma_f32_32x32x16_bf16 a[112:127], v[128:131], v[40:43], a[112:127]
	v_mfma_f32_32x32x16_bf16 a[128:143], v[128:131], v[120:123], a[128:143]
	s_waitcnt lgkmcnt(0)
	s_barrier
	ds_read_b128 v[44:47], v116 offset:0x8000
	ds_read_b128 v[48:51], v116 offset:0x8800
	ds_read_b128 v[52:55], v116 offset:0x9000
	ds_read_b128 v[56:59], v114 offset:0x8000
	v_mfma_f32_32x32x16_bf16 a[144:159], v[132:135], v[36:39], a[144:159]
	ds_read_b128 v[88:91], v114 offset:0x8800
	v_mfma_f32_32x32x16_bf16 a[160:175], v[132:135], v[40:43], a[160:175]
	ds_read_b128 v[92:95], v114 offset:0x9000
	v_add_u32_e32 v142, s8, v140
	v_add_u32_e32 v143, s8, v141
	global_load_dwordx4 v[4:7], v142, s[10:11]
	v_mfma_f32_32x32x16_bf16 a[176:191], v[132:135], v[120:123], a[176:191]
	ds_read_b128 v[96:99], v114 offset:0x9800
	global_load_dwordx4 v[8:11], v142, s[12:13]
	v_mfma_f32_32x32x16_bf16 a[32:47], v[136:139], v[36:39], a[32:47]
	global_load_dwordx4 v[12:15], v142, s[14:15]
	v_mfma_f32_32x32x16_bf16 a[16:31], v[136:139], v[40:43], a[16:31]
	global_load_dwordx4 v[16:19], v142, s[16:17]
	v_mfma_f32_32x32x16_bf16 a[0:15], v[136:139], v[120:123], a[0:15]
	global_load_dwordx4 v[20:23], v143, s[18:19]
	s_waitcnt lgkmcnt(3)
	v_mfma_f32_32x32x16_bf16 a[48:63], v[56:59], v[44:47], a[48:63]
	ds_read_b128 v[40:43], v117 offset:0x8000
	v_mfma_f32_32x32x16_bf16 a[64:79], v[56:59], v[48:51], a[64:79]
	global_load_dwordx4 v[24:27], v143, s[20:21]
	v_mfma_f32_32x32x16_bf16 a[80:95], v[56:59], v[52:55], a[80:95]
	ds_read_b128 v[36:39], v117 offset:0x8800
	s_waitcnt lgkmcnt(4)
	v_mfma_f32_32x32x16_bf16 a[96:111], v[88:91], v[44:47], a[96:111]
	global_load_dwordx4 v[28:31], v143, s[22:23]
	v_mfma_f32_32x32x16_bf16 a[112:127], v[88:91], v[48:51], a[112:127]
	ds_read_b128 v[194:197], v117 offset:0x9000
	v_mfma_f32_32x32x16_bf16 a[128:143], v[88:91], v[52:55], a[128:143]
	ds_read_b128 v[120:123], v115 offset:0x8000
	s_waitcnt lgkmcnt(5)
	v_mfma_f32_32x32x16_bf16 a[144:159], v[92:95], v[44:47], a[144:159]
	ds_read_b128 v[124:127], v115 offset:0x8800
	v_mfma_f32_32x32x16_bf16 a[160:175], v[92:95], v[48:51], a[160:175]
	ds_read_b128 v[128:131], v115 offset:0x9000
	v_mfma_f32_32x32x16_bf16 a[176:191], v[92:95], v[52:55], a[176:191]
	ds_read_b128 v[198:201], v115 offset:0x9800
	s_waitcnt lgkmcnt(7)
	v_mfma_f32_32x32x16_bf16 a[32:47], v[96:99], v[44:47], a[32:47]
	s_waitcnt vmcnt(13)
	ds_write_b128 v118, v[64:67] offset:0
	v_mfma_f32_32x32x16_bf16 a[16:31], v[96:99], v[48:51], a[16:31]
	s_waitcnt vmcnt(12)
	ds_write_b128 v118, v[60:63] offset:0x1000
	v_mfma_f32_32x32x16_bf16 a[0:15], v[96:99], v[52:55], a[0:15]
	s_waitcnt vmcnt(11)
	ds_write_b128 v118, v[72:75] offset:0x2000
	s_waitcnt lgkmcnt(6)
	v_mfma_f32_32x32x16_bf16 a[48:63], v[120:123], v[40:43], a[48:63]
	s_waitcnt vmcnt(10)
	ds_write_b128 v118, v[68:71] offset:0x3000
	v_mfma_f32_32x32x16_bf16 a[64:79], v[120:123], v[36:39], a[64:79]
	s_waitcnt vmcnt(9)
	ds_write_b128 v118, v[84:87] offset:0x4000
	v_mfma_f32_32x32x16_bf16 a[80:95], v[120:123], v[194:197], a[80:95]
	s_waitcnt vmcnt(8)
	ds_write_b128 v118, v[76:79] offset:0x5000
	s_waitcnt lgkmcnt(8)
	v_mfma_f32_32x32x16_bf16 a[96:111], v[124:127], v[40:43], a[96:111]
	s_waitcnt vmcnt(7)
	ds_write_b128 v118, v[80:83] offset:0x6000
	v_mfma_f32_32x32x16_bf16 a[112:127], v[124:127], v[36:39], a[112:127]
	v_mfma_f32_32x32x16_bf16 a[128:143], v[124:127], v[194:197], a[128:143]
	s_waitcnt lgkmcnt(0)
	s_barrier
	s_mov_b32 s6, s7
	.p2align 6

.LBB0_141:
	v_readfirstlane_b32 s8, v68
	v_readfirstlane_b32 s9, v69
	v_readfirstlane_b32 s10, v72
	v_readfirstlane_b32 s11, v73
	v_readfirstlane_b32 s12, v74
	v_readfirstlane_b32 s13, v75
	v_readfirstlane_b32 s14, v76
	v_readfirstlane_b32 s15, v77
	v_readfirstlane_b32 s16, v70
	v_readfirstlane_b32 s17, v71
	v_readfirstlane_b32 s18, v78
	v_readfirstlane_b32 s19, v79
	v_subrev_u32_e32 v144, s8, v68
	v_subrev_u32_e32 v145, s16, v70
	s_nop 4
	s_add_i32 s5, s4, 64
	s_min_u32 s6, s5, 0xae0
	s_lshl_b32 s78, s6, 1
	ds_read_b128 v[48:51], v82 offset:0
	ds_read_b128 v[44:47], v82 offset:0x800
	ds_read_b128 v[64:67], v80 offset:0
	ds_read_b128 v[60:63], v80 offset:0x800
	ds_read_b128 v[56:59], v80 offset:0x1000
	v_add_u32_e32 v146, s78, v144
	v_add_u32_e32 v147, s78, v145
	global_load_dwordx4 v[106:109], v146, s[8:9]
	ds_read_b128 v[52:55], v80 offset:0x1800
	global_load_dwordx4 v[110:113], v146, s[10:11]
	global_load_dwordx4 v[114:117], v146, s[12:13]
	s_waitcnt lgkmcnt(3)
	v_mfma_f32_32x32x16_bf16 a[32:47], v[64:67], v[48:51], 0
	ds_read_b128 v[40:43], v83 offset:0
	v_mfma_f32_32x32x16_bf16 a[48:63], v[64:67], v[44:47], 0
	global_load_dwordx4 v[118:121], v146, s[14:15]
	s_waitcnt lgkmcnt(3)
	v_mfma_f32_32x32x16_bf16 a[64:79], v[60:63], v[48:51], 0
	ds_read_b128 v[86:89], v83 offset:0x800
	v_mfma_f32_32x32x16_bf16 a[80:95], v[60:63], v[44:47], 0
	global_load_dwordx4 v[122:125], v147, s[16:17]
	s_waitcnt lgkmcnt(3)
	v_mfma_f32_32x32x16_bf16 a[96:111], v[56:59], v[48:51], 0
	ds_read_b128 v[90:93], v81 offset:0
	v_mfma_f32_32x32x16_bf16 a[112:127], v[56:59], v[44:47], 0
	global_load_dwordx4 v[140:143], v147, s[18:19]
	s_waitcnt vmcnt(11)
	ds_write_b128 v84, v[4:7] offset:0x8000
	s_waitcnt lgkmcnt(4)
	v_mfma_f32_32x32x16_bf16 a[16:31], v[52:55], v[48:51], 0
	ds_read_b128 v[94:97], v81 offset:0x800
	s_min_u32 s4, s4, 0xa80
	s_lshl_b32 s78, s4, 1
	s_waitcnt vmcnt(10)
	ds_write_b128 v84, v[8:11] offset:0x9000
	v_mfma_f32_32x32x16_bf16 a[0:15], v[52:55], v[44:47], 0
	ds_read_b128 v[98:101], v81 offset:0x1000
	s_add_i32 s6, s78, 0xc0
	s_mov_b32 s7, s79
	s_waitcnt vmcnt(9)
	ds_write_b128 v84, v[12:15] offset:0xa000
	s_waitcnt lgkmcnt(5)
	v_mfma_f32_32x32x16_bf16 a[32:47], v[90:93], v[40:43], a[32:47]
	ds_read_b128 v[102:105], v81 offset:0x1800
	s_add_i32 s3, s3, 2
	s_cmpk_lt_u32 s3, 0x56
	s_waitcnt vmcnt(8)
	ds_write_b128 v84, v[16:19] offset:0xb000
	v_mfma_f32_32x32x16_bf16 a[48:63], v[90:93], v[86:89], a[48:63]
	s_waitcnt vmcnt(7)
	ds_write_b128 v84, v[20:23] offset:0xc000
	s_waitcnt lgkmcnt(6)
	v_mfma_f32_32x32x16_bf16 a[64:79], v[94:97], v[40:43], a[64:79]
	s_waitcnt vmcnt(6)
	ds_write_b128 v84, v[24:27] offset:0xd000
	v_mfma_f32_32x32x16_bf16 a[80:95], v[94:97], v[86:89], a[80:95]
	s_waitcnt lgkmcnt(0)
	s_barrier
	ds_read_b128 v[44:47], v82 offset:0x8000
	ds_read_b128 v[48:51], v82 offset:0x8800
	ds_read_b128 v[52:55], v80 offset:0x8000
	v_mfma_f32_32x32x16_bf16 a[96:111], v[98:101], v[40:43], a[96:111]
	ds_read_b128 v[56:59], v80 offset:0x8800
	v_mfma_f32_32x32x16_bf16 a[112:127], v[98:101], v[86:89], a[112:127]
	ds_read_b128 v[60:63], v80 offset:0x9000
	v_add_u32_e32 v146, s6, v144
	v_add_u32_e32 v147, s6, v145
	global_load_dwordx4 v[4:7], v146, s[8:9]
	v_mfma_f32_32x32x16_bf16 a[16:31], v[102:105], v[40:43], a[16:31]
	ds_read_b128 v[64:67], v80 offset:0x9800
	global_load_dwordx4 v[8:11], v146, s[10:11]
	v_mfma_f32_32x32x16_bf16 a[0:15], v[102:105], v[86:89], a[0:15]
	global_load_dwordx4 v[12:15], v146, s[12:13]
	s_waitcnt lgkmcnt(3)
	v_mfma_f32_32x32x16_bf16 a[32:47], v[52:55], v[44:47], a[32:47]
	ds_read_b128 v[40:43], v83 offset:0x8000
	v_mfma_f32_32x32x16_bf16 a[48:63], v[52:55], v[48:51], a[48:63]
	global_load_dwordx4 v[16:19], v146, s[14:15]
	s_waitcnt lgkmcnt(3)
	v_mfma_f32_32x32x16_bf16 a[64:79], v[56:59], v[44:47], a[64:79]
	ds_read_b128 v[128:131], v83 offset:0x8800
	v_mfma_f32_32x32x16_bf16 a[80:95], v[56:59], v[48:51], a[80:95]
	global_load_dwordx4 v[20:23], v147, s[16:17]
	s_waitcnt lgkmcnt(3)
	v_mfma_f32_32x32x16_bf16 a[96:111], v[60:63], v[44:47], a[96:111]
	ds_read_b128 v[86:89], v81 offset:0x8000
	v_mfma_f32_32x32x16_bf16 a[112:127], v[60:63], v[48:51], a[112:127]
	global_load_dwordx4 v[24:27], v147, s[18:19]
	s_waitcnt vmcnt(11)
	ds_write_b128 v84, v[106:109] offset:0
	s_waitcnt lgkmcnt(4)
	v_mfma_f32_32x32x16_bf16 a[16:31], v[64:67], v[44:47], a[16:31]
	ds_read_b128 v[90:93], v81 offset:0x8800
	s_waitcnt vmcnt(10)
	ds_write_b128 v84, v[110:113] offset:0x1000
	v_mfma_f32_32x32x16_bf16 a[0:15], v[64:67], v[48:51], a[0:15]
	ds_read_b128 v[94:97], v81 offset:0x9000
	s_waitcnt vmcnt(9)
	ds_write_b128 v84, v[114:117] offset:0x2000
	s_waitcnt lgkmcnt(5)
	v_mfma_f32_32x32x16_bf16 a[32:47], v[86:89], v[40:43], a[32:47]
	ds_read_b128 v[132:135], v81 offset:0x9800
	s_waitcnt vmcnt(8)
	ds_write_b128 v84, v[118:121] offset:0x3000
	v_mfma_f32_32x32x16_bf16 a[48:63], v[86:89], v[128:131], a[48:63]
	s_waitcnt vmcnt(7)
	ds_write_b128 v84, v[122:125] offset:0x4000
	s_waitcnt lgkmcnt(6)
	v_mfma_f32_32x32x16_bf16 a[64:79], v[90:93], v[40:43], a[64:79]
	s_waitcnt vmcnt(6)
	ds_write_b128 v84, v[140:143] offset:0x5000
	v_mfma_f32_32x32x16_bf16 a[80:95], v[90:93], v[128:131], a[80:95]
	s_waitcnt lgkmcnt(0)
	s_barrier
	s_mov_b32 s4, s5
	.p2align 6

.LBB0_162:
	v_readfirstlane_b32 s8, v96
	v_readfirstlane_b32 s9, v97
	v_readfirstlane_b32 s10, v100
	v_readfirstlane_b32 s11, v101
	v_readfirstlane_b32 s12, v102
	v_readfirstlane_b32 s13, v103
	v_readfirstlane_b32 s14, v104
	v_readfirstlane_b32 s15, v105
	v_readfirstlane_b32 s16, v98
	v_readfirstlane_b32 s17, v99
	v_readfirstlane_b32 s18, v106
	v_readfirstlane_b32 s19, v107
	v_readfirstlane_b32 s20, v108
	v_readfirstlane_b32 s21, v109
	v_subrev_u32_e32 v140, s8, v96
	v_subrev_u32_e32 v141, s16, v98
	s_nop 4
	s_add_i32 s5, s4, 64
	s_min_u32 s6, s5, 0x3e0
	s_lshl_b32 s78, s6, 1
	ds_read_b128 v[44:47], v116 offset:0
	ds_read_b128 v[40:43], v116 offset:0x800
	ds_read_b128 v[36:39], v116 offset:0x1000
	ds_read_b128 v[92:95], v110 offset:0
	ds_read_b128 v[88:91], v110 offset:0x800
	ds_read_b128 v[84:87], v110 offset:0x1000
	v_add_u32_e32 v142, s78, v140
	v_add_u32_e32 v143, s78, v141
	global_load_dwordx4 v[56:59], v142, s[8:9]
	ds_read_b128 v[48:51], v110 offset:0x1800
	global_load_dwordx4 v[52:55], v142, s[10:11]
	global_load_dwordx4 v[64:67], v142, s[12:13]
	global_load_dwordx4 v[60:63], v142, s[14:15]
	global_load_dwordx4 v[76:79], v143, s[16:17]
	s_waitcnt lgkmcnt(3)
	v_mfma_f32_32x32x16_bf16 a[80:95], v[92:95], v[44:47], 0
	ds_read_b128 v[80:83], v117 offset:0
	v_mfma_f32_32x32x16_bf16 a[48:63], v[92:95], v[40:43], 0
	global_load_dwordx4 v[68:71], v143, s[18:19]
	v_mfma_f32_32x32x16_bf16 a[64:79], v[92:95], v[36:39], 0
	ds_read_b128 v[112:115], v117 offset:0x800
	s_waitcnt lgkmcnt(4)
	v_mfma_f32_32x32x16_bf16 a[96:111], v[88:91], v[44:47], 0
	global_load_dwordx4 v[72:75], v143, s[20:21]
	v_mfma_f32_32x32x16_bf16 a[112:127], v[88:91], v[40:43], 0
	ds_read_b128 v[120:123], v117 offset:0x1000
	v_mfma_f32_32x32x16_bf16 a[128:143], v[88:91], v[36:39], 0
	ds_read_b128 v[124:127], v111 offset:0
	s_waitcnt lgkmcnt(5)
	v_mfma_f32_32x32x16_bf16 a[144:159], v[84:87], v[44:47], 0
	ds_read_b128 v[128:131], v111 offset:0x800
	s_min_u32 s4, s4, 0x380
	s_lshl_b32 s78, s4, 1
	v_mfma_f32_32x32x16_bf16 a[160:175], v[84:87], v[40:43], 0
	ds_read_b128 v[132:135], v111 offset:0x1000
	s_add_i32 s6, s78, 0xc0
	s_mov_b32 s7, s79
	v_mfma_f32_32x32x16_bf16 a[176:191], v[84:87], v[36:39], 0
	ds_read_b128 v[136:139], v111 offset:0x1800
	s_add_i32 s3, s3, 2
	s_cmp_lt_u32 s3, 30
	s_waitcnt lgkmcnt(7)
	v_mfma_f32_32x32x16_bf16 a[32:47], v[48:51], v[44:47], 0
	s_waitcnt vmcnt(13)
	ds_write_b128 v118, v[4:7] offset:0x8000
	v_mfma_f32_32x32x16_bf16 a[16:31], v[48:51], v[40:43], 0
	s_waitcnt vmcnt(12)
	ds_write_b128 v118, v[8:11] offset:0x9000
	v_mfma_f32_32x32x16_bf16 a[0:15], v[48:51], v[36:39], 0
	s_waitcnt vmcnt(11)
	ds_write_b128 v118, v[12:15] offset:0xa000
	s_waitcnt lgkmcnt(6)
	v_mfma_f32_32x32x16_bf16 a[80:95], v[124:127], v[80:83], a[80:95]
	s_waitcnt vmcnt(10)
	ds_write_b128 v118, v[16:19] offset:0xb000
	v_mfma_f32_32x32x16_bf16 a[48:63], v[124:127], v[112:115], a[48:63]
	s_waitcnt vmcnt(9)
	ds_write_b128 v118, v[20:23] offset:0xc000
	v_mfma_f32_32x32x16_bf16 a[64:79], v[124:127], v[120:123], a[64:79]
	s_waitcnt vmcnt(8)
	ds_write_b128 v118, v[24:27] offset:0xd000
	s_waitcnt lgkmcnt(8)
	v_mfma_f32_32x32x16_bf16 a[96:111], v[128:131], v[80:83], a[96:111]
	s_waitcnt vmcnt(7)
	ds_write_b128 v118, v[28:31] offset:0xe000
	v_mfma_f32_32x32x16_bf16 a[112:127], v[128:131], v[112:115], a[112:127]
	v_mfma_f32_32x32x16_bf16 a[128:143], v[128:131], v[120:123], a[128:143]
	s_waitcnt lgkmcnt(0)
	s_barrier
	ds_read_b128 v[36:39], v116 offset:0x8000
	ds_read_b128 v[40:43], v116 offset:0x8800
	ds_read_b128 v[44:47], v116 offset:0x9000
	ds_read_b128 v[48:51], v110 offset:0x8000
	v_mfma_f32_32x32x16_bf16 a[144:159], v[132:135], v[80:83], a[144:159]
	ds_read_b128 v[84:87], v110 offset:0x8800
	v_mfma_f32_32x32x16_bf16 a[160:175], v[132:135], v[112:115], a[160:175]
	ds_read_b128 v[88:91], v110 offset:0x9000
	v_add_u32_e32 v142, s6, v140
	v_add_u32_e32 v143, s6, v141
	global_load_dwordx4 v[4:7], v142, s[8:9]
	v_mfma_f32_32x32x16_bf16 a[176:191], v[132:135], v[120:123], a[176:191]
	ds_read_b128 v[92:95], v110 offset:0x9800
	global_load_dwordx4 v[8:11], v142, s[10:11]
	v_mfma_f32_32x32x16_bf16 a[32:47], v[136:139], v[80:83], a[32:47]
	global_load_dwordx4 v[12:15], v142, s[12:13]
	v_mfma_f32_32x32x16_bf16 a[16:31], v[136:139], v[112:115], a[16:31]
	global_load_dwordx4 v[16:19], v142, s[14:15]
	v_mfma_f32_32x32x16_bf16 a[0:15], v[136:139], v[120:123], a[0:15]
	global_load_dwordx4 v[20:23], v143, s[16:17]
	s_waitcnt lgkmcnt(3)
	v_mfma_f32_32x32x16_bf16 a[80:95], v[48:51], v[36:39], a[80:95]
	ds_read_b128 v[80:83], v117 offset:0x8000
	v_mfma_f32_32x32x16_bf16 a[48:63], v[48:51], v[40:43], a[48:63]
	global_load_dwordx4 v[24:27], v143, s[18:19]
	v_mfma_f32_32x32x16_bf16 a[64:79], v[48:51], v[44:47], a[64:79]
	ds_read_b128 v[112:115], v117 offset:0x8800
	s_waitcnt lgkmcnt(4)
	v_mfma_f32_32x32x16_bf16 a[96:111], v[84:87], v[36:39], a[96:111]
	global_load_dwordx4 v[28:31], v143, s[20:21]
	v_mfma_f32_32x32x16_bf16 a[112:127], v[84:87], v[40:43], a[112:127]
	ds_read_b128 v[128:131], v117 offset:0x9000
	v_mfma_f32_32x32x16_bf16 a[128:143], v[84:87], v[44:47], a[128:143]
	ds_read_b128 v[120:123], v111 offset:0x8000
	s_waitcnt lgkmcnt(5)
	v_mfma_f32_32x32x16_bf16 a[144:159], v[88:91], v[36:39], a[144:159]
	ds_read_b128 v[124:127], v111 offset:0x8800
	v_mfma_f32_32x32x16_bf16 a[160:175], v[88:91], v[40:43], a[160:175]
	ds_read_b128 v[136:139], v111 offset:0x9000
	v_mfma_f32_32x32x16_bf16 a[176:191], v[88:91], v[44:47], a[176:191]
	ds_read_b128 v[132:135], v111 offset:0x9800
	s_waitcnt lgkmcnt(7)
	v_mfma_f32_32x32x16_bf16 a[32:47], v[92:95], v[36:39], a[32:47]
	s_waitcnt vmcnt(13)
	ds_write_b128 v118, v[56:59] offset:0
	v_mfma_f32_32x32x16_bf16 a[16:31], v[92:95], v[40:43], a[16:31]
	s_waitcnt vmcnt(12)
	ds_write_b128 v118, v[52:55] offset:0x1000
	v_mfma_f32_32x32x16_bf16 a[0:15], v[92:95], v[44:47], a[0:15]
	s_waitcnt vmcnt(11)
	ds_write_b128 v118, v[64:67] offset:0x2000
	s_waitcnt lgkmcnt(6)
	v_mfma_f32_32x32x16_bf16 a[80:95], v[120:123], v[80:83], a[80:95]
	s_waitcnt vmcnt(10)
	ds_write_b128 v118, v[60:63] offset:0x3000
	v_mfma_f32_32x32x16_bf16 a[48:63], v[120:123], v[112:115], a[48:63]
	s_waitcnt vmcnt(9)
	ds_write_b128 v118, v[76:79] offset:0x4000
	v_mfma_f32_32x32x16_bf16 a[64:79], v[120:123], v[128:131], a[64:79]
	s_waitcnt vmcnt(8)
	ds_write_b128 v118, v[68:71] offset:0x5000
	s_waitcnt lgkmcnt(8)
	v_mfma_f32_32x32x16_bf16 a[96:111], v[124:127], v[80:83], a[96:111]
	s_waitcnt vmcnt(7)
	ds_write_b128 v118, v[72:75] offset:0x6000
	v_mfma_f32_32x32x16_bf16 a[112:127], v[124:127], v[112:115], a[112:127]
	v_mfma_f32_32x32x16_bf16 a[128:143], v[124:127], v[128:131], a[128:143]
	s_waitcnt lgkmcnt(0)
	s_barrier
	s_mov_b32 s4, s5
	.p2align 6

.LBB0_205:
	v_readfirstlane_b32 s10, v100
	v_readfirstlane_b32 s11, v101
	v_readfirstlane_b32 s12, v104
	v_readfirstlane_b32 s13, v105
	v_readfirstlane_b32 s14, v106
	v_readfirstlane_b32 s15, v107
	v_readfirstlane_b32 s16, v108
	v_readfirstlane_b32 s17, v109
	v_readfirstlane_b32 s18, v102
	v_readfirstlane_b32 s19, v103
	v_readfirstlane_b32 s20, v110
	v_readfirstlane_b32 s21, v111
	v_readfirstlane_b32 s22, v112
	v_readfirstlane_b32 s23, v113
	v_subrev_u32_e32 v140, s10, v100
	v_subrev_u32_e32 v141, s18, v102
	s_nop 4
	s_add_i32 s7, s6, 64
	s_min_u32 s8, s7, 0x3e0
	s_lshl_b32 s78, s8, 1
	ds_read_b128 v[52:55], v116 offset:0
	ds_read_b128 v[48:51], v116 offset:0x800
	ds_read_b128 v[44:47], v116 offset:0x1000
	ds_read_b128 v[96:99], v114 offset:0
	ds_read_b128 v[92:95], v114 offset:0x800
	ds_read_b128 v[88:91], v114 offset:0x1000
	v_add_u32_e32 v142, s78, v140
	v_add_u32_e32 v143, s78, v141
	global_load_dwordx4 v[64:67], v142, s[10:11]
	ds_read_b128 v[56:59], v114 offset:0x1800
	global_load_dwordx4 v[60:63], v142, s[12:13]
	global_load_dwordx4 v[72:75], v142, s[14:15]
	global_load_dwordx4 v[68:71], v142, s[16:17]
	global_load_dwordx4 v[84:87], v143, s[18:19]
	s_waitcnt lgkmcnt(3)
	v_mfma_f32_32x32x16_bf16 a[48:63], v[96:99], v[52:55], 0
	ds_read_b128 v[36:39], v117 offset:0
	v_mfma_f32_32x32x16_bf16 a[64:79], v[96:99], v[48:51], 0
	global_load_dwordx4 v[76:79], v143, s[20:21]
	v_mfma_f32_32x32x16_bf16 a[80:95], v[96:99], v[44:47], 0
	ds_read_b128 v[40:43], v117 offset:0x800
	s_waitcnt lgkmcnt(4)
	v_mfma_f32_32x32x16_bf16 a[96:111], v[92:95], v[52:55], 0
	global_load_dwordx4 v[80:83], v143, s[22:23]
	v_mfma_f32_32x32x16_bf16 a[112:127], v[92:95], v[48:51], 0
	ds_read_b128 v[120:123], v117 offset:0x1000
	v_mfma_f32_32x32x16_bf16 a[128:143], v[92:95], v[44:47], 0
	ds_read_b128 v[124:127], v115 offset:0
	s_waitcnt lgkmcnt(5)
	v_mfma_f32_32x32x16_bf16 a[144:159], v[88:91], v[52:55], 0
	ds_read_b128 v[128:131], v115 offset:0x800
	s_min_u32 s6, s6, 0x380
	s_lshl_b32 s78, s6, 1
	v_mfma_f32_32x32x16_bf16 a[160:175], v[88:91], v[48:51], 0
	ds_read_b128 v[132:135], v115 offset:0x1000
	s_add_i32 s8, s78, 0xc0
	s_mov_b32 s9, s79
	v_mfma_f32_32x32x16_bf16 a[176:191], v[88:91], v[44:47], 0
	ds_read_b128 v[136:139], v115 offset:0x1800
	s_add_i32 s5, s5, 2
	s_cmp_lt_u32 s5, 30
	s_waitcnt lgkmcnt(7)
	v_mfma_f32_32x32x16_bf16 a[32:47], v[56:59], v[52:55], 0
	s_waitcnt vmcnt(13)
	ds_write_b128 v118, v[4:7] offset:0x8000
	v_mfma_f32_32x32x16_bf16 a[16:31], v[56:59], v[48:51], 0
	s_waitcnt vmcnt(12)
	ds_write_b128 v118, v[8:11] offset:0x9000
	v_mfma_f32_32x32x16_bf16 a[0:15], v[56:59], v[44:47], 0
	s_waitcnt vmcnt(11)
	ds_write_b128 v118, v[12:15] offset:0xa000
	s_waitcnt lgkmcnt(6)
	v_mfma_f32_32x32x16_bf16 a[48:63], v[124:127], v[36:39], a[48:63]
	s_waitcnt vmcnt(10)
	ds_write_b128 v118, v[16:19] offset:0xb000
	v_mfma_f32_32x32x16_bf16 a[64:79], v[124:127], v[40:43], a[64:79]
	s_waitcnt vmcnt(9)
	ds_write_b128 v118, v[20:23] offset:0xc000
	v_mfma_f32_32x32x16_bf16 a[80:95], v[124:127], v[120:123], a[80:95]
	s_waitcnt vmcnt(8)
	ds_write_b128 v118, v[24:27] offset:0xd000
	s_waitcnt lgkmcnt(8)
	v_mfma_f32_32x32x16_bf16 a[96:111], v[128:131], v[36:39], a[96:111]
	s_waitcnt vmcnt(7)
	ds_write_b128 v118, v[28:31] offset:0xe000
	v_mfma_f32_32x32x16_bf16 a[112:127], v[128:131], v[40:43], a[112:127]
	v_mfma_f32_32x32x16_bf16 a[128:143], v[128:131], v[120:123], a[128:143]
	s_waitcnt lgkmcnt(0)
	s_barrier
	ds_read_b128 v[44:47], v116 offset:0x8000
	ds_read_b128 v[48:51], v116 offset:0x8800
	ds_read_b128 v[52:55], v116 offset:0x9000
	ds_read_b128 v[56:59], v114 offset:0x8000
	v_mfma_f32_32x32x16_bf16 a[144:159], v[132:135], v[36:39], a[144:159]
	ds_read_b128 v[88:91], v114 offset:0x8800
	v_mfma_f32_32x32x16_bf16 a[160:175], v[132:135], v[40:43], a[160:175]
	ds_read_b128 v[92:95], v114 offset:0x9000
	v_add_u32_e32 v142, s8, v140
	v_add_u32_e32 v143, s8, v141
	global_load_dwordx4 v[4:7], v142, s[10:11]
	v_mfma_f32_32x32x16_bf16 a[176:191], v[132:135], v[120:123], a[176:191]
	ds_read_b128 v[96:99], v114 offset:0x9800
	global_load_dwordx4 v[8:11], v142, s[12:13]
	v_mfma_f32_32x32x16_bf16 a[32:47], v[136:139], v[36:39], a[32:47]
	global_load_dwordx4 v[12:15], v142, s[14:15]
	v_mfma_f32_32x32x16_bf16 a[16:31], v[136:139], v[40:43], a[16:31]
	global_load_dwordx4 v[16:19], v142, s[16:17]
	v_mfma_f32_32x32x16_bf16 a[0:15], v[136:139], v[120:123], a[0:15]
	global_load_dwordx4 v[20:23], v143, s[18:19]
	s_waitcnt lgkmcnt(3)
	v_mfma_f32_32x32x16_bf16 a[48:63], v[56:59], v[44:47], a[48:63]
	ds_read_b128 v[40:43], v117 offset:0x8000
	v_mfma_f32_32x32x16_bf16 a[64:79], v[56:59], v[48:51], a[64:79]
	global_load_dwordx4 v[24:27], v143, s[20:21]
	v_mfma_f32_32x32x16_bf16 a[80:95], v[56:59], v[52:55], a[80:95]
	ds_read_b128 v[36:39], v117 offset:0x8800
	s_waitcnt lgkmcnt(4)
	v_mfma_f32_32x32x16_bf16 a[96:111], v[88:91], v[44:47], a[96:111]
	global_load_dwordx4 v[28:31], v143, s[22:23]
	v_mfma_f32_32x32x16_bf16 a[112:127], v[88:91], v[48:51], a[112:127]
	ds_read_b128 v[194:197], v117 offset:0x9000
	v_mfma_f32_32x32x16_bf16 a[128:143], v[88:91], v[52:55], a[128:143]
	ds_read_b128 v[120:123], v115 offset:0x8000
	s_waitcnt lgkmcnt(5)
	v_mfma_f32_32x32x16_bf16 a[144:159], v[92:95], v[44:47], a[144:159]
	ds_read_b128 v[124:127], v115 offset:0x8800
	v_mfma_f32_32x32x16_bf16 a[160:175], v[92:95], v[48:51], a[160:175]
	ds_read_b128 v[128:131], v115 offset:0x9000
	v_mfma_f32_32x32x16_bf16 a[176:191], v[92:95], v[52:55], a[176:191]
	ds_read_b128 v[198:201], v115 offset:0x9800
	s_waitcnt lgkmcnt(7)
	v_mfma_f32_32x32x16_bf16 a[32:47], v[96:99], v[44:47], a[32:47]
	s_waitcnt vmcnt(13)
	ds_write_b128 v118, v[64:67] offset:0
	v_mfma_f32_32x32x16_bf16 a[16:31], v[96:99], v[48:51], a[16:31]
	s_waitcnt vmcnt(12)
	ds_write_b128 v118, v[60:63] offset:0x1000
	v_mfma_f32_32x32x16_bf16 a[0:15], v[96:99], v[52:55], a[0:15]
	s_waitcnt vmcnt(11)
	ds_write_b128 v118, v[72:75] offset:0x2000
	s_waitcnt lgkmcnt(6)
	v_mfma_f32_32x32x16_bf16 a[48:63], v[120:123], v[40:43], a[48:63]
	s_waitcnt vmcnt(10)
	ds_write_b128 v118, v[68:71] offset:0x3000
	v_mfma_f32_32x32x16_bf16 a[64:79], v[120:123], v[36:39], a[64:79]
	s_waitcnt vmcnt(9)
	ds_write_b128 v118, v[84:87] offset:0x4000
	v_mfma_f32_32x32x16_bf16 a[80:95], v[120:123], v[194:197], a[80:95]
	s_waitcnt vmcnt(8)
	ds_write_b128 v118, v[76:79] offset:0x5000
	s_waitcnt lgkmcnt(8)
	v_mfma_f32_32x32x16_bf16 a[96:111], v[124:127], v[40:43], a[96:111]
	s_waitcnt vmcnt(7)
	ds_write_b128 v118, v[80:83] offset:0x6000
	v_mfma_f32_32x32x16_bf16 a[112:127], v[124:127], v[36:39], a[112:127]
	v_mfma_f32_32x32x16_bf16 a[128:143], v[124:127], v[194:197], a[128:143]
	s_waitcnt lgkmcnt(0)
	s_barrier
	s_mov_b32 s6, s7
	.p2align 6

.LBB0_224:
	v_readfirstlane_b32 s8, v68
	v_readfirstlane_b32 s9, v69
	v_readfirstlane_b32 s10, v72
	v_readfirstlane_b32 s11, v73
	v_readfirstlane_b32 s12, v74
	v_readfirstlane_b32 s13, v75
	v_readfirstlane_b32 s14, v76
	v_readfirstlane_b32 s15, v77
	v_readfirstlane_b32 s16, v70
	v_readfirstlane_b32 s17, v71
	v_readfirstlane_b32 s18, v78
	v_readfirstlane_b32 s19, v79
	v_subrev_u32_e32 v144, s8, v68
	v_subrev_u32_e32 v145, s16, v70
	s_nop 4
	s_add_i32 s5, s4, 64
	s_min_u32 s6, s5, 0x3e0
	s_lshl_b32 s78, s6, 1
	ds_read_b128 v[48:51], v82 offset:0
	ds_read_b128 v[44:47], v82 offset:0x800
	ds_read_b128 v[64:67], v80 offset:0
	ds_read_b128 v[60:63], v80 offset:0x800
	ds_read_b128 v[56:59], v80 offset:0x1000
	v_add_u32_e32 v146, s78, v144
	v_add_u32_e32 v147, s78, v145
	global_load_dwordx4 v[106:109], v146, s[8:9]
	ds_read_b128 v[52:55], v80 offset:0x1800
	global_load_dwordx4 v[110:113], v146, s[10:11]
	global_load_dwordx4 v[114:117], v146, s[12:13]
	s_waitcnt lgkmcnt(3)
	v_mfma_f32_32x32x16_bf16 a[32:47], v[64:67], v[48:51], 0
	ds_read_b128 v[40:43], v83 offset:0
	v_mfma_f32_32x32x16_bf16 a[48:63], v[64:67], v[44:47], 0
	global_load_dwordx4 v[118:121], v146, s[14:15]
	s_waitcnt lgkmcnt(3)
	v_mfma_f32_32x32x16_bf16 a[64:79], v[60:63], v[48:51], 0
	ds_read_b128 v[86:89], v83 offset:0x800
	v_mfma_f32_32x32x16_bf16 a[80:95], v[60:63], v[44:47], 0
	global_load_dwordx4 v[122:125], v147, s[16:17]
	s_waitcnt lgkmcnt(3)
	v_mfma_f32_32x32x16_bf16 a[96:111], v[56:59], v[48:51], 0
	ds_read_b128 v[90:93], v81 offset:0
	v_mfma_f32_32x32x16_bf16 a[112:127], v[56:59], v[44:47], 0
	global_load_dwordx4 v[140:143], v147, s[18:19]
	s_waitcnt vmcnt(11)
	ds_write_b128 v84, v[4:7] offset:0x8000
	s_waitcnt lgkmcnt(4)
	v_mfma_f32_32x32x16_bf16 a[16:31], v[52:55], v[48:51], 0
	ds_read_b128 v[94:97], v81 offset:0x800
	s_min_u32 s4, s4, 0x380
	s_lshl_b32 s78, s4, 1
	s_waitcnt vmcnt(10)
	ds_write_b128 v84, v[8:11] offset:0x9000
	v_mfma_f32_32x32x16_bf16 a[0:15], v[52:55], v[44:47], 0
	ds_read_b128 v[98:101], v81 offset:0x1000
	s_add_i32 s6, s78, 0xc0
	s_mov_b32 s7, s79
	s_waitcnt vmcnt(9)
	ds_write_b128 v84, v[12:15] offset:0xa000
	s_waitcnt lgkmcnt(5)
	v_mfma_f32_32x32x16_bf16 a[32:47], v[90:93], v[40:43], a[32:47]
	ds_read_b128 v[102:105], v81 offset:0x1800
	s_add_i32 s3, s3, 2
	s_cmp_lt_u32 s3, 30
	s_waitcnt vmcnt(8)
	ds_write_b128 v84, v[16:19] offset:0xb000
	v_mfma_f32_32x32x16_bf16 a[48:63], v[90:93], v[86:89], a[48:63]
	s_waitcnt vmcnt(7)
	ds_write_b128 v84, v[20:23] offset:0xc000
	s_waitcnt lgkmcnt(6)
	v_mfma_f32_32x32x16_bf16 a[64:79], v[94:97], v[40:43], a[64:79]
	s_waitcnt vmcnt(6)
	ds_write_b128 v84, v[24:27] offset:0xd000
	v_mfma_f32_32x32x16_bf16 a[80:95], v[94:97], v[86:89], a[80:95]
	s_waitcnt lgkmcnt(0)
	s_barrier
	ds_read_b128 v[44:47], v82 offset:0x8000
	ds_read_b128 v[48:51], v82 offset:0x8800
	ds_read_b128 v[52:55], v80 offset:0x8000
	v_mfma_f32_32x32x16_bf16 a[96:111], v[98:101], v[40:43], a[96:111]
	ds_read_b128 v[56:59], v80 offset:0x8800
	v_mfma_f32_32x32x16_bf16 a[112:127], v[98:101], v[86:89], a[112:127]
	ds_read_b128 v[60:63], v80 offset:0x9000
	v_add_u32_e32 v146, s6, v144
	v_add_u32_e32 v147, s6, v145
	global_load_dwordx4 v[4:7], v146, s[8:9]
	v_mfma_f32_32x32x16_bf16 a[16:31], v[102:105], v[40:43], a[16:31]
	ds_read_b128 v[64:67], v80 offset:0x9800
	global_load_dwordx4 v[8:11], v146, s[10:11]
	v_mfma_f32_32x32x16_bf16 a[0:15], v[102:105], v[86:89], a[0:15]
	global_load_dwordx4 v[12:15], v146, s[12:13]
	s_waitcnt lgkmcnt(3)
	v_mfma_f32_32x32x16_bf16 a[32:47], v[52:55], v[44:47], a[32:47]
	ds_read_b128 v[40:43], v83 offset:0x8000
	v_mfma_f32_32x32x16_bf16 a[48:63], v[52:55], v[48:51], a[48:63]
	global_load_dwordx4 v[16:19], v146, s[14:15]
	s_waitcnt lgkmcnt(3)
	v_mfma_f32_32x32x16_bf16 a[64:79], v[56:59], v[44:47], a[64:79]
	ds_read_b128 v[128:131], v83 offset:0x8800
	v_mfma_f32_32x32x16_bf16 a[80:95], v[56:59], v[48:51], a[80:95]
	global_load_dwordx4 v[20:23], v147, s[16:17]
	s_waitcnt lgkmcnt(3)
	v_mfma_f32_32x32x16_bf16 a[96:111], v[60:63], v[44:47], a[96:111]
	ds_read_b128 v[86:89], v81 offset:0x8000
	v_mfma_f32_32x32x16_bf16 a[112:127], v[60:63], v[48:51], a[112:127]
	global_load_dwordx4 v[24:27], v147, s[18:19]
	s_waitcnt vmcnt(11)
	ds_write_b128 v84, v[106:109] offset:0
	s_waitcnt lgkmcnt(4)
	v_mfma_f32_32x32x16_bf16 a[16:31], v[64:67], v[44:47], a[16:31]
	ds_read_b128 v[90:93], v81 offset:0x8800
	s_waitcnt vmcnt(10)
	ds_write_b128 v84, v[110:113] offset:0x1000
	v_mfma_f32_32x32x16_bf16 a[0:15], v[64:67], v[48:51], a[0:15]
	ds_read_b128 v[94:97], v81 offset:0x9000
	s_waitcnt vmcnt(9)
	ds_write_b128 v84, v[114:117] offset:0x2000
	s_waitcnt lgkmcnt(5)
	v_mfma_f32_32x32x16_bf16 a[32:47], v[86:89], v[40:43], a[32:47]
	ds_read_b128 v[132:135], v81 offset:0x9800
	s_waitcnt vmcnt(8)
	ds_write_b128 v84, v[118:121] offset:0x3000
	v_mfma_f32_32x32x16_bf16 a[48:63], v[86:89], v[128:131], a[48:63]
	s_waitcnt vmcnt(7)
	ds_write_b128 v84, v[122:125] offset:0x4000
	s_waitcnt lgkmcnt(6)
	v_mfma_f32_32x32x16_bf16 a[64:79], v[90:93], v[40:43], a[64:79]
	s_waitcnt vmcnt(6)
	ds_write_b128 v84, v[140:143] offset:0x5000
	v_mfma_f32_32x32x16_bf16 a[80:95], v[90:93], v[128:131], a[80:95]
	s_waitcnt lgkmcnt(0)
	s_barrier
	s_mov_b32 s4, s5
	.p2align 6

.LBB0_773:
	v_readfirstlane_b32 s8, v64
	v_readfirstlane_b32 s9, v65
	v_readfirstlane_b32 s10, v68
	v_readfirstlane_b32 s11, v69
	v_readfirstlane_b32 s12, v70
	v_readfirstlane_b32 s13, v71
	v_readfirstlane_b32 s14, v72
	v_readfirstlane_b32 s15, v73
	v_readfirstlane_b32 s16, v66
	v_readfirstlane_b32 s17, v67
	v_readfirstlane_b32 s18, v74
	v_readfirstlane_b32 s19, v75
	v_subrev_u32_e32 v140, s8, v64
	v_subrev_u32_e32 v141, s16, v66
	s_nop 4
	s_add_i32 s4, s3, 64
	s_min_u32 s5, s4, 0x3e0
	s_lshl_b32 s78, s5, 1
	ds_read_b128 v[44:47], v78 offset:0
	ds_read_b128 v[40:43], v78 offset:0x800
	ds_read_b128 v[60:63], v76 offset:0
	ds_read_b128 v[56:59], v76 offset:0x800
	ds_read_b128 v[52:55], v76 offset:0x1000
	v_add_u32_e32 v142, s78, v140
	v_add_u32_e32 v143, s78, v141
	global_load_dwordx4 v[106:109], v142, s[8:9]
	ds_read_b128 v[48:51], v76 offset:0x1800
	global_load_dwordx4 v[110:113], v142, s[10:11]
	global_load_dwordx4 v[114:117], v142, s[12:13]
	s_waitcnt lgkmcnt(3)
	v_mfma_f32_32x32x16_bf16 a[112:127], v[60:63], v[44:47], 0
	ds_read_b128 v[82:85], v79 offset:0
	v_mfma_f32_32x32x16_bf16 a[96:111], v[60:63], v[40:43], 0
	global_load_dwordx4 v[118:121], v142, s[14:15]
	s_waitcnt lgkmcnt(3)
	v_mfma_f32_32x32x16_bf16 a[80:95], v[56:59], v[44:47], 0
	ds_read_b128 v[86:89], v79 offset:0x800
	v_mfma_f32_32x32x16_bf16 a[64:79], v[56:59], v[40:43], 0
	global_load_dwordx4 v[122:125], v143, s[16:17]
	s_waitcnt lgkmcnt(3)
	v_mfma_f32_32x32x16_bf16 a[48:63], v[52:55], v[44:47], 0
	ds_read_b128 v[90:93], v77 offset:0
	v_mfma_f32_32x32x16_bf16 a[16:31], v[52:55], v[40:43], 0
	global_load_dwordx4 v[126:129], v143, s[18:19]
	s_waitcnt vmcnt(11)
	ds_write_b128 v80, v[4:7] offset:0x8000
	s_waitcnt lgkmcnt(4)
	v_mfma_f32_32x32x16_bf16 a[0:15], v[48:51], v[44:47], 0
	ds_read_b128 v[94:97], v77 offset:0x800
	s_min_u32 s3, s3, 0x380
	s_lshl_b32 s78, s3, 1
	s_waitcnt vmcnt(10)
	ds_write_b128 v80, v[8:11] offset:0x9000
	v_mfma_f32_32x32x16_bf16 a[128:143], v[48:51], v[40:43], 0
	ds_read_b128 v[98:101], v77 offset:0x1000
	s_add_i32 s6, s78, 0xc0
	s_mov_b32 s7, s79
	s_waitcnt vmcnt(9)
	ds_write_b128 v80, v[12:15] offset:0xa000
	s_waitcnt lgkmcnt(5)
	v_mfma_f32_32x32x16_bf16 a[112:127], v[90:93], v[82:85], a[112:127]
	ds_read_b128 v[102:105], v77 offset:0x1800
	s_add_i32 s2, s2, 2
	s_cmp_gt_u32 s2, 29
	s_waitcnt vmcnt(8)
	ds_write_b128 v80, v[16:19] offset:0xb000
	v_mfma_f32_32x32x16_bf16 a[96:111], v[90:93], v[86:89], a[96:111]
	s_waitcnt vmcnt(7)
	ds_write_b128 v80, v[20:23] offset:0xc000
	s_waitcnt lgkmcnt(6)
	v_mfma_f32_32x32x16_bf16 a[80:95], v[94:97], v[82:85], a[80:95]
	s_waitcnt vmcnt(6)
	ds_write_b128 v80, v[24:27] offset:0xd000
	v_mfma_f32_32x32x16_bf16 a[64:79], v[94:97], v[86:89], a[64:79]
	s_waitcnt lgkmcnt(0)
	s_barrier
	ds_read_b128 v[40:43], v78 offset:0x8000
	ds_read_b128 v[44:47], v78 offset:0x8800
	ds_read_b128 v[48:51], v76 offset:0x8000
	v_mfma_f32_32x32x16_bf16 a[48:63], v[98:101], v[82:85], a[48:63]
	ds_read_b128 v[52:55], v76 offset:0x8800
	v_mfma_f32_32x32x16_bf16 a[16:31], v[98:101], v[86:89], a[16:31]
	ds_read_b128 v[56:59], v76 offset:0x9000
	v_add_u32_e32 v142, s6, v140
	v_add_u32_e32 v143, s6, v141
	global_load_dwordx4 v[4:7], v142, s[8:9]
	v_mfma_f32_32x32x16_bf16 a[0:15], v[102:105], v[82:85], a[0:15]
	ds_read_b128 v[60:63], v76 offset:0x9800
	global_load_dwordx4 v[8:11], v142, s[10:11]
	v_mfma_f32_32x32x16_bf16 a[128:143], v[102:105], v[86:89], a[128:143]
	global_load_dwordx4 v[12:15], v142, s[12:13]
	s_waitcnt lgkmcnt(3)
	v_mfma_f32_32x32x16_bf16 a[112:127], v[48:51], v[40:43], a[112:127]
	ds_read_b128 v[202:205], v79 offset:0x8000
	v_mfma_f32_32x32x16_bf16 a[96:111], v[48:51], v[44:47], a[96:111]
	global_load_dwordx4 v[16:19], v142, s[14:15]
	s_waitcnt lgkmcnt(3)
	v_mfma_f32_32x32x16_bf16 a[80:95], v[52:55], v[40:43], a[80:95]
	ds_read_b128 v[194:197], v79 offset:0x8800
	v_mfma_f32_32x32x16_bf16 a[64:79], v[52:55], v[44:47], a[64:79]
	global_load_dwordx4 v[20:23], v143, s[16:17]
	s_waitcnt lgkmcnt(3)
	v_mfma_f32_32x32x16_bf16 a[48:63], v[56:59], v[40:43], a[48:63]
	ds_read_b128 v[82:85], v77 offset:0x8000
	v_mfma_f32_32x32x16_bf16 a[16:31], v[56:59], v[44:47], a[16:31]
	global_load_dwordx4 v[24:27], v143, s[18:19]
	s_waitcnt vmcnt(11)
	ds_write_b128 v80, v[106:109] offset:0
	s_waitcnt lgkmcnt(4)
	v_mfma_f32_32x32x16_bf16 a[0:15], v[60:63], v[40:43], a[0:15]
	ds_read_b128 v[86:89], v77 offset:0x8800
	s_waitcnt vmcnt(10)
	ds_write_b128 v80, v[110:113] offset:0x1000
	v_mfma_f32_32x32x16_bf16 a[128:143], v[60:63], v[44:47], a[128:143]
	ds_read_b128 v[90:93], v77 offset:0x9000
	s_waitcnt vmcnt(9)
	ds_write_b128 v80, v[114:117] offset:0x2000
	s_waitcnt lgkmcnt(5)
	v_mfma_f32_32x32x16_bf16 a[112:127], v[82:85], v[202:205], a[112:127]
	ds_read_b128 v[198:201], v77 offset:0x9800
	s_waitcnt vmcnt(8)
	ds_write_b128 v80, v[118:121] offset:0x3000
	v_mfma_f32_32x32x16_bf16 a[96:111], v[82:85], v[194:197], a[96:111]
	s_waitcnt vmcnt(7)
	ds_write_b128 v80, v[122:125] offset:0x4000
	s_waitcnt lgkmcnt(6)
	v_mfma_f32_32x32x16_bf16 a[80:95], v[86:89], v[202:205], a[80:95]
	s_waitcnt vmcnt(6)
	ds_write_b128 v80, v[126:129] offset:0x5000
	v_mfma_f32_32x32x16_bf16 a[64:79], v[86:89], v[194:197], a[64:79]
	s_waitcnt lgkmcnt(0)
	s_barrier
	s_mov_b32 s3, s4
	.p2align 6
